# rstd_table at the GU / input-projection phase starts: per-thread last row address and value remembered, repeated rows skip the four loads and the arithmetic (wave-uniform), 6 dependent round trips bec
# speedup vs baseline: 1.0035x; 1.0035x over previous
.LBB0_560:
	s_cmp_eq_u32 s2, 0
	s_cbranch_scc1 .LBB0_581
	v_readlane_b32 s0, v254, 26
	s_lshl_b32 s0, s0, 21
	s_lshl_b32 s18, s2, 8
	s_bitset1_b32 s0, 24
	s_add_u32 s0, s58, s0
	v_lshlrev_b32_e32 v0, 6, v166
	s_addc_u32 s1, s59, 0
	v_and_b32_e32 v0, 0x3fc0, v0
	v_lshl_add_u64 v[2:3], s[0:1], 0, v[0:1]
	s_mov_b64 s[0:1], 0x28c00000
	v_lshl_add_u64 v[4:5], v[2:3], 0, s[0:1]
	s_add_i32 s0, 0, 0x20000
	v_lshl_add_u32 v10, v166, 2, s0
	s_mov_b32 s19, 0
	v_mov_b32_e32 v6, s5
	v_mov_b32_e32 v28, 0
	v_mov_b32_e32 v29, 0
	s_branch .LBB0_563

.LBB0_566:
	s_or_b64 exec, exec, s[0:1]
	v_ashrrev_i32_e32 v7, 31, v6
	v_lshlrev_b64 v[2:3], 14, v[6:7]
	v_lshl_add_u64 v[2:3], v[4:5], 0, v[2:3]
	v_cmp_ne_u64_e32 vcc, v[2:3], v[28:29]
	s_cbranch_vccz .Lrstd_same_0
	v_mov_b32_e32 v28, v2
	v_mov_b32_e32 v29, v3
	global_load_dwordx4 v[12:15], v[2:3], off
	global_load_dwordx4 v[16:19], v[2:3], off offset:16
	global_load_dwordx4 v[20:23], v[2:3], off offset:32
	global_load_dwordx4 v[24:27], v[2:3], off offset:48
	s_waitcnt vmcnt(0) lgkmcnt(0)
	v_mov_b32_e32 v2, v13
	v_mov_b32_e32 v3, v14
	v_mov_b32_e32 v13, v15
	v_pk_add_f32 v[2:3], v[2:3], v[12:13]
	v_mov_b32_e32 v12, v17
	v_mov_b32_e32 v13, v18
	v_mov_b32_e32 v17, v19
	v_pk_add_f32 v[12:13], v[12:13], v[16:17]
	v_pk_add_f32 v[2:3], v[2:3], v[2:3] op_sel:[0,1] op_sel_hi:[1,0]
	v_pk_add_f32 v[12:13], v[12:13], v[12:13] op_sel:[0,1] op_sel_hi:[1,0]
	v_add_f32_e32 v14, v20, v21
	v_add_f32_e32 v16, v22, v23
	v_mov_b32_e32 v3, v24
	v_mov_b32_e32 v13, v25
	v_mov_b32_e32 v15, v26
	v_mov_b32_e32 v17, v27
	v_pk_add_f32 v[2:3], v[2:3], v[12:13]
	v_pk_add_f32 v[12:13], v[14:15], v[16:17]
	s_nop 0
	v_pk_add_f32 v[2:3], v[2:3], v[12:13]
	s_nop 0
	v_add_f32_e32 v0, v2, v3
	v_fmamk_f32 v0, v0, 0x3a800000, v218
	v_cmp_gt_f32_e32 vcc, s79, v0
	v_mul_f32_e32 v2, 0x4f800000, v0
	s_nop 0
	v_cndmask_b32_e32 v0, v0, v2, vcc
	v_sqrt_f32_e32 v2, v0
	s_nop 0
	v_add_u32_e32 v3, -1, v2
	v_fma_f32 v7, -v3, v2, v0
	v_cmp_ge_f32_e64 s[0:1], 0, v7
	v_add_u32_e32 v7, 1, v2
	s_nop 0
	v_cndmask_b32_e64 v3, v2, v3, s[0:1]
	v_fma_f32 v2, -v7, v2, v0
	v_cmp_lt_f32_e64 s[0:1], 0, v2
	s_nop 1
	v_cndmask_b32_e64 v2, v3, v7, s[0:1]
	v_mul_f32_e32 v3, 0x37800000, v2
	v_cndmask_b32_e32 v2, v2, v3, vcc
	v_cmp_class_f32_e32 vcc, v0, v205
	s_nop 1
	v_cndmask_b32_e32 v0, v2, v0, vcc
	v_div_scale_f32 v2, s[0:1], v0, v0, 1.0
	v_rcp_f32_e32 v3, v2
	s_nop 0
	v_fma_f32 v7, -v2, v3, 1.0
	v_fmac_f32_e32 v3, v7, v3
	v_div_scale_f32 v7, vcc, 1.0, v0, 1.0
	v_mul_f32_e32 v9, v7, v3
	v_fma_f32 v11, -v2, v9, v7
	v_fmac_f32_e32 v9, v11, v3
	v_fma_f32 v2, -v2, v9, v7
	v_div_fmas_f32 v2, v2, v3, v9
	v_div_fixup_f32 v0, v2, v0, 1.0
	v_mov_b32_e32 v30, v0
	s_branch .Lrstd_done_0
.Lrstd_same_0:
	v_mov_b32_e32 v0, v30
.Lrstd_done_0:
.LBB0_567:
	s_or_b64 exec, exec, s[4:5]
	v_add_u32_e32 v2, 0x200, v8
	v_mov_b32_e32 v3, s95
	v_cmp_gt_i32_e64 s[4:5], s18, v2
	s_and_saveexec_b64 s[6:7], s[4:5]
	s_cbranch_execz .LBB0_571
	v_ashrrev_i32_e32 v7, 8, v2
	v_mov_b64_e32 v[2:3], s[80:81]
	v_mad_i64_i32 v[2:3], s[0:1], v7, s63, v[2:3]
	v_cmp_gt_i64_e32 vcc, s[94:95], v[2:3]
	s_and_saveexec_b64 s[0:1], vcc
	s_cbranch_execz .LBB0_570
	v_ashrrev_i32_e32 v3, 31, v2
	v_lshrrev_b32_e32 v3, 29, v3
	v_add_u32_e32 v3, v2, v3
	v_ashrrev_i32_e32 v6, 3, v3
	v_and_b32_e32 v3, -8, v3
	v_sub_u32_e32 v2, v2, v3
	v_mov_b32_e32 v3, s57
	v_mov_b32_e32 v7, s92
	v_cmp_gt_i32_e32 vcc, 0, v2
	s_nop 1
	v_cndmask_b32_e32 v3, v3, v7, vcc
	v_mul_lo_u32 v2, v3, v2
	v_add_u32_e32 v2, v2, v6
	v_sub_u32_e32 v6, 0, v2
	v_max_i32_e32 v6, v2, v6
	v_mul_hi_u32 v7, v6, s93
	v_mul_lo_u32 v9, v7, s13
	v_sub_u32_e32 v6, v6, v9
	v_add_u32_e32 v9, 1, v7
	v_cmp_le_u32_e32 vcc, s13, v6
	v_ashrrev_i32_e32 v3, 31, v2
	s_nop 0
	v_cndmask_b32_e32 v7, v7, v9, vcc
	v_subrev_u32_e32 v9, s13, v6
	v_cndmask_b32_e32 v6, v6, v9, vcc
	v_add_u32_e32 v9, 1, v7
	v_cmp_le_u32_e32 vcc, s13, v6
	s_nop 1
	v_cndmask_b32_e32 v6, v7, v9, vcc
	v_xor_b32_e32 v6, v6, v3
	v_sub_u32_e32 v3, v6, v3
	v_lshlrev_b32_e32 v6, 3, v3
	v_sub_u32_e32 v7, 0x80, v6
	v_min_i32_e32 v7, 8, v7
	v_sub_u32_e32 v9, 0, v7
	v_max_i32_e32 v7, v7, v9
	v_cvt_f32_u32_e32 v9, v7
	v_mul_lo_u32 v3, v3, s13
	v_sub_u32_e32 v2, v2, v3
	v_sub_u32_e32 v11, 0, v2
	v_rcp_iflag_f32_e32 v9, v9
	v_ashrrev_i32_e32 v3, 31, v2
	v_max_i32_e32 v2, v2, v11
	v_sub_u32_e32 v11, 0, v7
	v_mul_f32_e32 v9, 0x4f7ffffe, v9
	v_cvt_u32_f32_e32 v9, v9
	v_mul_lo_u32 v11, v11, v9
	v_mul_hi_u32 v11, v9, v11
	v_add_u32_e32 v9, v9, v11
	v_mul_hi_u32 v9, v2, v9
	v_mul_lo_u32 v9, v9, v7
	v_sub_u32_e32 v2, v2, v9
	v_sub_u32_e32 v9, v2, v7
	v_cmp_ge_u32_e32 vcc, v2, v7
	s_nop 1
	v_cndmask_b32_e32 v2, v2, v9, vcc
	v_sub_u32_e32 v9, v2, v7
	v_cmp_ge_u32_e32 vcc, v2, v7
	s_nop 1
	v_cndmask_b32_e32 v2, v2, v9, vcc
	v_xor_b32_e32 v2, v2, v3
	v_sub_u32_e32 v2, v2, v3
	v_add_u32_e32 v6, v2, v6
.LBB0_570:
	s_or_b64 exec, exec, s[0:1]
	v_ashrrev_i32_e32 v7, 31, v6
	v_lshlrev_b64 v[2:3], 14, v[6:7]
	v_lshl_add_u64 v[2:3], v[4:5], 0, v[2:3]
	v_cmp_ne_u64_e32 vcc, v[2:3], v[28:29]
	s_cbranch_vccz .Lrstd_same_1
	v_mov_b32_e32 v28, v2
	v_mov_b32_e32 v29, v3
	global_load_dwordx4 v[12:15], v[2:3], off
	global_load_dwordx4 v[16:19], v[2:3], off offset:16
	global_load_dwordx4 v[20:23], v[2:3], off offset:32
	global_load_dwordx4 v[24:27], v[2:3], off offset:48
	s_waitcnt vmcnt(0) lgkmcnt(0)
	v_mov_b32_e32 v2, v13
	v_mov_b32_e32 v3, v14
	v_mov_b32_e32 v13, v15
	v_pk_add_f32 v[2:3], v[2:3], v[12:13]
	v_mov_b32_e32 v12, v17
	v_mov_b32_e32 v13, v18
	v_mov_b32_e32 v17, v19
	v_pk_add_f32 v[12:13], v[12:13], v[16:17]
	v_pk_add_f32 v[2:3], v[2:3], v[2:3] op_sel:[0,1] op_sel_hi:[1,0]
	v_pk_add_f32 v[12:13], v[12:13], v[12:13] op_sel:[0,1] op_sel_hi:[1,0]
	v_add_f32_e32 v14, v20, v21
	v_add_f32_e32 v16, v22, v23
	v_mov_b32_e32 v3, v24
	v_mov_b32_e32 v13, v25
	v_mov_b32_e32 v15, v26
	v_mov_b32_e32 v17, v27
	v_pk_add_f32 v[2:3], v[2:3], v[12:13]
	v_pk_add_f32 v[12:13], v[14:15], v[16:17]
	s_nop 0
	v_pk_add_f32 v[2:3], v[2:3], v[12:13]
	s_nop 0
	v_add_f32_e32 v2, v2, v3
	v_fmamk_f32 v2, v2, 0x3a800000, v218
	v_cmp_gt_f32_e32 vcc, s79, v2
	v_mul_f32_e32 v3, 0x4f800000, v2
	s_nop 0
	v_cndmask_b32_e32 v2, v2, v3, vcc
	v_sqrt_f32_e32 v3, v2
	s_nop 0
	v_add_u32_e32 v7, -1, v3
	v_fma_f32 v9, -v7, v3, v2
	v_cmp_ge_f32_e64 s[0:1], 0, v9
	v_add_u32_e32 v9, 1, v3
	s_nop 0
	v_cndmask_b32_e64 v7, v3, v7, s[0:1]
	v_fma_f32 v3, -v9, v3, v2
	v_cmp_lt_f32_e64 s[0:1], 0, v3
	s_nop 1
	v_cndmask_b32_e64 v3, v7, v9, s[0:1]
	v_mul_f32_e32 v7, 0x37800000, v3
	v_cndmask_b32_e32 v3, v3, v7, vcc
	v_cmp_class_f32_e32 vcc, v2, v205
	s_nop 1
	v_cndmask_b32_e32 v2, v3, v2, vcc
	v_div_scale_f32 v3, s[0:1], v2, v2, 1.0
	v_rcp_f32_e32 v7, v3
	s_nop 0
	v_fma_f32 v9, -v3, v7, 1.0
	v_fmac_f32_e32 v7, v9, v7
	v_div_scale_f32 v9, vcc, 1.0, v2, 1.0
	v_mul_f32_e32 v11, v9, v7
	v_fma_f32 v12, -v3, v11, v9
	v_fmac_f32_e32 v11, v12, v7
	v_fma_f32 v3, -v3, v11, v9
	v_div_fmas_f32 v3, v3, v7, v11
	v_div_fixup_f32 v3, v3, v2, 1.0
	v_mov_b32_e32 v30, v3
	s_branch .Lrstd_done_1
.Lrstd_same_1:
	v_mov_b32_e32 v3, v30
.Lrstd_done_1:
.LBB0_571:
	s_or_b64 exec, exec, s[6:7]
	v_add_u32_e32 v7, 0x400, v8
	v_mov_b32_e32 v2, s95
	v_cmp_gt_i32_e64 s[0:1], s18, v7
	s_and_saveexec_b64 s[16:17], s[0:1]
	s_cbranch_execz .LBB0_577
	v_ashrrev_i32_e32 v2, 8, v7
	v_mov_b64_e32 v[8:9], s[80:81]
	v_mad_i64_i32 v[8:9], s[6:7], v2, s63, v[8:9]
	v_cmp_gt_i64_e32 vcc, s[94:95], v[8:9]
	s_and_saveexec_b64 s[6:7], vcc
	s_cbranch_execz .LBB0_574
	v_ashrrev_i32_e32 v2, 31, v8
	v_lshrrev_b32_e32 v2, 29, v2
	v_add_u32_e32 v2, v8, v2
	v_ashrrev_i32_e32 v6, 3, v2
	v_and_b32_e32 v2, -8, v2
	v_sub_u32_e32 v2, v8, v2
	v_mov_b32_e32 v7, s57
	v_mov_b32_e32 v8, s92
	v_cmp_gt_i32_e32 vcc, 0, v2
	s_nop 1
	v_cndmask_b32_e32 v7, v7, v8, vcc
	v_mul_lo_u32 v2, v7, v2
	v_add_u32_e32 v2, v2, v6
	v_sub_u32_e32 v7, 0, v2
	v_max_i32_e32 v7, v2, v7
	v_mul_hi_u32 v8, v7, s93
	v_mul_lo_u32 v9, v8, s13
	v_sub_u32_e32 v7, v7, v9
	v_add_u32_e32 v9, 1, v8
	v_cmp_le_u32_e32 vcc, s13, v7
	v_ashrrev_i32_e32 v6, 31, v2
	s_nop 0
	v_cndmask_b32_e32 v8, v8, v9, vcc
	v_subrev_u32_e32 v9, s13, v7
	v_cndmask_b32_e32 v7, v7, v9, vcc
	v_add_u32_e32 v9, 1, v8
	v_cmp_le_u32_e32 vcc, s13, v7
	s_nop 1
	v_cndmask_b32_e32 v7, v8, v9, vcc
	v_xor_b32_e32 v7, v7, v6
	v_sub_u32_e32 v6, v7, v6
	v_lshlrev_b32_e32 v7, 3, v6
	v_sub_u32_e32 v8, 0x80, v7
	v_min_i32_e32 v8, 8, v8
	v_sub_u32_e32 v9, 0, v8
	v_max_i32_e32 v8, v8, v9
	v_cvt_f32_u32_e32 v9, v8
	v_mul_lo_u32 v6, v6, s13
	v_sub_u32_e32 v2, v2, v6
	v_sub_u32_e32 v11, 0, v2
	v_rcp_iflag_f32_e32 v9, v9
	v_ashrrev_i32_e32 v6, 31, v2
	v_max_i32_e32 v2, v2, v11
	v_sub_u32_e32 v11, 0, v8
	v_mul_f32_e32 v9, 0x4f7ffffe, v9
	v_cvt_u32_f32_e32 v9, v9
	v_mul_lo_u32 v11, v11, v9
	v_mul_hi_u32 v11, v9, v11
	v_add_u32_e32 v9, v9, v11
	v_mul_hi_u32 v9, v2, v9
	v_mul_lo_u32 v9, v9, v8
	v_sub_u32_e32 v2, v2, v9
	v_sub_u32_e32 v9, v2, v8
	v_cmp_ge_u32_e32 vcc, v2, v8
	s_nop 1
	v_cndmask_b32_e32 v2, v2, v9, vcc
	v_sub_u32_e32 v9, v2, v8
	v_cmp_ge_u32_e32 vcc, v2, v8
	s_nop 1
	v_cndmask_b32_e32 v2, v2, v9, vcc
	v_xor_b32_e32 v2, v2, v6
	v_sub_u32_e32 v2, v2, v6
	v_add_u32_e32 v6, v2, v7
.LBB0_574:
	s_or_b64 exec, exec, s[6:7]
	v_ashrrev_i32_e32 v7, 31, v6
	v_lshlrev_b64 v[8:9], 14, v[6:7]
	v_lshl_add_u64 v[8:9], v[4:5], 0, v[8:9]
	v_cmp_ne_u64_e32 vcc, v[8:9], v[28:29]
	s_cbranch_vccz .Lrstd_same_2
	v_mov_b32_e32 v28, v8
	v_mov_b32_e32 v29, v9
	global_load_dwordx4 v[12:15], v[8:9], off
	global_load_dwordx4 v[16:19], v[8:9], off offset:16
	global_load_dwordx4 v[20:23], v[8:9], off offset:32
	global_load_dwordx4 v[24:27], v[8:9], off offset:48
	s_waitcnt vmcnt(0) lgkmcnt(0)
	v_mov_b32_e32 v8, v13
	v_mov_b32_e32 v9, v14
	v_mov_b32_e32 v13, v15
	v_pk_add_f32 v[8:9], v[8:9], v[12:13]
	v_mov_b32_e32 v12, v17
	v_mov_b32_e32 v13, v18
	v_mov_b32_e32 v17, v19
	v_pk_add_f32 v[12:13], v[12:13], v[16:17]
	v_pk_add_f32 v[8:9], v[8:9], v[8:9] op_sel:[0,1] op_sel_hi:[1,0]
	v_pk_add_f32 v[12:13], v[12:13], v[12:13] op_sel:[0,1] op_sel_hi:[1,0]
	v_add_f32_e32 v14, v20, v21
	v_add_f32_e32 v16, v22, v23
	v_mov_b32_e32 v9, v24
	v_mov_b32_e32 v13, v25
	v_mov_b32_e32 v15, v26
	v_mov_b32_e32 v17, v27
	v_pk_add_f32 v[8:9], v[8:9], v[12:13]
	v_pk_add_f32 v[12:13], v[14:15], v[16:17]
	s_nop 0
	v_pk_add_f32 v[8:9], v[8:9], v[12:13]
	s_nop 0
	v_add_f32_e32 v2, v8, v9
	v_fmamk_f32 v2, v2, 0x3a800000, v218
	v_cmp_gt_f32_e32 vcc, s79, v2
	v_mul_f32_e32 v7, 0x4f800000, v2
	s_nop 0
	v_cndmask_b32_e32 v2, v2, v7, vcc
	v_sqrt_f32_e32 v7, v2
	s_nop 0
	v_add_u32_e32 v8, -1, v7
	v_fma_f32 v9, -v8, v7, v2
	v_cmp_ge_f32_e64 s[6:7], 0, v9
	v_add_u32_e32 v9, 1, v7
	s_nop 0
	v_cndmask_b32_e64 v8, v7, v8, s[6:7]
	v_fma_f32 v7, -v9, v7, v2
	v_cmp_lt_f32_e64 s[6:7], 0, v7
	s_nop 1
	v_cndmask_b32_e64 v7, v8, v9, s[6:7]
	v_mul_f32_e32 v8, 0x37800000, v7
	v_cndmask_b32_e32 v7, v7, v8, vcc
	v_cmp_class_f32_e32 vcc, v2, v205
	s_nop 1
	v_cndmask_b32_e32 v2, v7, v2, vcc
	v_div_scale_f32 v7, s[6:7], v2, v2, 1.0
	v_rcp_f32_e32 v8, v7
	s_nop 0
	v_fma_f32 v9, -v7, v8, 1.0
	v_fmac_f32_e32 v8, v9, v8
	v_div_scale_f32 v9, vcc, 1.0, v2, 1.0
	v_mul_f32_e32 v11, v9, v8
	v_fma_f32 v12, -v7, v11, v9
	v_fmac_f32_e32 v11, v12, v8
	v_fma_f32 v7, -v7, v11, v9
	v_div_fmas_f32 v7, v7, v8, v11
	v_div_fixup_f32 v2, v7, v2, 1.0
	v_mov_b32_e32 v30, v2
	s_branch .Lrstd_done_2
.Lrstd_same_2:
	v_mov_b32_e32 v2, v30
.Lrstd_done_2:
	s_or_b64 exec, exec, s[16:17]
	s_and_saveexec_b64 s[6:7], s[2:3]
	s_cbranch_execnz .LBB0_578

.LBB0_930:
	s_cmp_eq_u32 s2, 0
	s_cbranch_scc1 .LBB0_951
	s_mov_b32 s19, s95
	s_lshl_b32 s10, s2, 8
	s_lshl_b64 s[0:1], s[18:19], 21
	s_add_u32 s0, s58, s0
	v_lshlrev_b32_e32 v0, 6, v166
	s_addc_u32 s1, s59, s1
	v_and_b32_e32 v0, 0x3fc0, v0
	s_waitcnt lgkmcnt(0)
	v_lshl_add_u64 v[2:3], s[0:1], 0, v[0:1]
	s_mov_b64 s[0:1], 0x28c00000
	v_lshl_add_u64 v[4:5], v[2:3], 0, s[0:1]
	s_add_i32 s0, 0, 0x20000
	v_lshl_add_u32 v10, v166, 2, s0
	s_mov_b32 s11, 0
	v_mov_b32_e32 v6, s5
	v_mov_b32_e32 v28, 0
	v_mov_b32_e32 v29, 0
	s_branch .LBB0_933

.LBB0_936:
	s_or_b64 exec, exec, s[0:1]
	v_ashrrev_i32_e32 v7, 31, v6
	v_lshlrev_b64 v[2:3], 14, v[6:7]
	v_lshl_add_u64 v[2:3], v[4:5], 0, v[2:3]
	v_cmp_ne_u64_e32 vcc, v[2:3], v[28:29]
	s_cbranch_vccz .Lrstd_same_3
	v_mov_b32_e32 v28, v2
	v_mov_b32_e32 v29, v3
	global_load_dwordx4 v[12:15], v[2:3], off
	global_load_dwordx4 v[16:19], v[2:3], off offset:16
	global_load_dwordx4 v[20:23], v[2:3], off offset:32
	global_load_dwordx4 v[24:27], v[2:3], off offset:48
	s_waitcnt vmcnt(0) lgkmcnt(0)
	v_mov_b32_e32 v2, v13
	v_mov_b32_e32 v3, v14
	v_mov_b32_e32 v13, v15
	v_mov_b32_e32 v14, v17
	v_mov_b32_e32 v15, v18
	v_mov_b32_e32 v17, v19
	v_pk_add_f32 v[2:3], v[2:3], v[12:13]
	v_pk_add_f32 v[12:13], v[14:15], v[16:17]
	v_pk_add_f32 v[2:3], v[2:3], v[2:3] op_sel:[0,1] op_sel_hi:[1,0]
	v_pk_add_f32 v[12:13], v[12:13], v[12:13] op_sel:[0,1] op_sel_hi:[1,0]
	v_add_f32_e32 v18, v20, v21
	v_add_f32_e32 v20, v22, v23
	v_mov_b32_e32 v19, v26
	v_mov_b32_e32 v21, v27
	v_mov_b32_e32 v3, v24
	v_mov_b32_e32 v13, v25
	v_pk_add_f32 v[14:15], v[18:19], v[20:21]
	v_pk_add_f32 v[2:3], v[2:3], v[12:13]
	s_nop 0
	v_pk_add_f32 v[2:3], v[2:3], v[14:15]
	s_nop 0
	v_add_f32_e32 v0, v2, v3
	v_fmamk_f32 v0, v0, 0x3a800000, v218
	v_mul_f32_e32 v2, 0x4f800000, v0
	v_cmp_gt_f32_e32 vcc, s79, v0
	s_nop 1
	v_cndmask_b32_e32 v0, v0, v2, vcc
	v_sqrt_f32_e32 v2, v0
	s_nop 0
	v_add_u32_e32 v3, -1, v2
	v_add_u32_e32 v7, 1, v2
	v_fma_f32 v9, -v3, v2, v0
	v_fma_f32 v11, -v7, v2, v0
	v_cmp_ge_f32_e64 s[0:1], 0, v9
	s_nop 1
	v_cndmask_b32_e64 v2, v2, v3, s[0:1]
	v_cmp_lt_f32_e64 s[0:1], 0, v11
	s_nop 1
	v_cndmask_b32_e64 v2, v2, v7, s[0:1]
	v_mul_f32_e32 v3, 0x37800000, v2
	v_cndmask_b32_e32 v2, v2, v3, vcc
	v_cmp_class_f32_e32 vcc, v0, v205
	s_nop 1
	v_cndmask_b32_e32 v0, v2, v0, vcc
	v_div_scale_f32 v2, s[0:1], v0, v0, 1.0
	v_rcp_f32_e32 v3, v2
	v_div_scale_f32 v7, vcc, 1.0, v0, 1.0
	v_fma_f32 v9, -v2, v3, 1.0
	v_fmac_f32_e32 v3, v9, v3
	v_mul_f32_e32 v9, v7, v3
	v_fma_f32 v11, -v2, v9, v7
	v_fmac_f32_e32 v9, v11, v3
	v_fma_f32 v2, -v2, v9, v7
	v_div_fmas_f32 v2, v2, v3, v9
	v_div_fixup_f32 v0, v2, v0, 1.0
	v_mov_b32_e32 v30, v0
	s_branch .Lrstd_done_3

.Lrstd_done_3:
.LBB0_937:
	s_or_b64 exec, exec, s[4:5]
	v_add_u32_e32 v2, 0x200, v8
	v_mov_b32_e32 v3, s95
	v_cmp_gt_i32_e64 s[0:1], s10, v2
	s_and_saveexec_b64 s[6:7], s[0:1]
	s_cbranch_execz .LBB0_941
	v_ashrrev_i32_e32 v7, 8, v2
	v_mov_b64_e32 v[2:3], s[80:81]
	v_mad_i64_i32 v[2:3], s[4:5], v7, s63, v[2:3]
	s_mov_b64 s[4:5], 0xb00
	s_nop 0
	v_cmp_gt_i64_e32 vcc, s[4:5], v[2:3]
	s_and_saveexec_b64 s[4:5], vcc
	s_cbranch_execz .LBB0_940
	v_ashrrev_i32_e32 v3, 31, v2
	v_lshrrev_b32_e32 v3, 29, v3
	v_add_u32_e32 v3, v2, v3
	v_ashrrev_i32_e32 v6, 3, v3
	v_and_b32_e32 v3, -8, v3
	v_sub_u32_e32 v2, v2, v3
	v_cmp_gt_i32_e32 vcc, 0, v2
	s_mov_b32 s8, 0x2e8ba2e9
	s_nop 0
	v_cndmask_b32_e32 v3, v233, v234, vcc
	v_mul_lo_u32 v2, v2, v3
	v_add_u32_e32 v2, v2, v6
	v_mul_hi_i32 v3, v2, s8
	v_lshrrev_b32_e32 v6, 31, v3
	v_ashrrev_i32_e32 v3, 5, v3
	v_add_u32_e32 v3, v3, v6
	v_lshlrev_b32_e32 v6, 3, v3
	v_sub_u32_e32 v7, 0x80, v6
	v_min_i32_e32 v7, 8, v7
	v_sub_u32_e32 v9, 0, v7
	v_max_i32_e32 v7, v7, v9
	v_cvt_f32_u32_e32 v9, v7
	s_movk_i32 s8, 0xb0
	v_mul_lo_u32 v3, v3, s8
	v_sub_u32_e32 v2, v2, v3
	v_rcp_iflag_f32_e32 v9, v9
	v_sub_u32_e32 v11, 0, v2
	v_ashrrev_i32_e32 v3, 31, v2
	v_max_i32_e32 v2, v2, v11
	v_mul_f32_e32 v9, 0x4f7ffffe, v9
	v_cvt_u32_f32_e32 v9, v9
	v_sub_u32_e32 v11, 0, v7
	v_mul_lo_u32 v11, v11, v9
	v_mul_hi_u32 v11, v9, v11
	v_add_u32_e32 v9, v9, v11
	v_mul_hi_u32 v9, v2, v9
	v_mul_lo_u32 v9, v9, v7
	v_sub_u32_e32 v2, v2, v9
	v_sub_u32_e32 v9, v2, v7
	v_cmp_ge_u32_e32 vcc, v2, v7
	s_nop 1
	v_cndmask_b32_e32 v2, v2, v9, vcc
	v_sub_u32_e32 v9, v2, v7
	v_cmp_ge_u32_e32 vcc, v2, v7
	s_nop 1
	v_cndmask_b32_e32 v2, v2, v9, vcc
	v_xor_b32_e32 v2, v2, v3
	v_sub_u32_e32 v2, v2, v3
	v_add_u32_e32 v6, v6, v2
.LBB0_940:
	s_or_b64 exec, exec, s[4:5]
	v_ashrrev_i32_e32 v7, 31, v6
	v_lshlrev_b64 v[2:3], 14, v[6:7]
	v_lshl_add_u64 v[2:3], v[4:5], 0, v[2:3]
	v_cmp_ne_u64_e32 vcc, v[2:3], v[28:29]
	s_cbranch_vccz .Lrstd_same_4
	v_mov_b32_e32 v28, v2
	v_mov_b32_e32 v29, v3
	global_load_dwordx4 v[12:15], v[2:3], off
	global_load_dwordx4 v[16:19], v[2:3], off offset:16
	global_load_dwordx4 v[20:23], v[2:3], off offset:32
	global_load_dwordx4 v[24:27], v[2:3], off offset:48
	s_waitcnt vmcnt(0) lgkmcnt(0)
	v_mov_b32_e32 v2, v13
	v_mov_b32_e32 v3, v14
	v_mov_b32_e32 v13, v15
	v_mov_b32_e32 v14, v17
	v_mov_b32_e32 v15, v18
	v_mov_b32_e32 v17, v19
	v_pk_add_f32 v[2:3], v[2:3], v[12:13]
	v_pk_add_f32 v[12:13], v[14:15], v[16:17]
	v_pk_add_f32 v[2:3], v[2:3], v[2:3] op_sel:[0,1] op_sel_hi:[1,0]
	v_pk_add_f32 v[12:13], v[12:13], v[12:13] op_sel:[0,1] op_sel_hi:[1,0]
	v_add_f32_e32 v18, v20, v21
	v_add_f32_e32 v20, v22, v23
	v_mov_b32_e32 v19, v26
	v_mov_b32_e32 v21, v27
	v_mov_b32_e32 v3, v24
	v_mov_b32_e32 v13, v25
	v_pk_add_f32 v[14:15], v[18:19], v[20:21]
	v_pk_add_f32 v[2:3], v[2:3], v[12:13]
	s_nop 0
	v_pk_add_f32 v[2:3], v[2:3], v[14:15]
	s_nop 0
	v_add_f32_e32 v2, v2, v3
	v_fmamk_f32 v2, v2, 0x3a800000, v218
	v_mul_f32_e32 v3, 0x4f800000, v2
	v_cmp_gt_f32_e32 vcc, s79, v2
	s_nop 1
	v_cndmask_b32_e32 v2, v2, v3, vcc
	v_sqrt_f32_e32 v3, v2
	s_nop 0
	v_add_u32_e32 v7, -1, v3
	v_add_u32_e32 v9, 1, v3
	v_fma_f32 v11, -v7, v3, v2
	v_fma_f32 v12, -v9, v3, v2
	v_cmp_ge_f32_e64 s[4:5], 0, v11
	s_nop 1
	v_cndmask_b32_e64 v3, v3, v7, s[4:5]
	v_cmp_lt_f32_e64 s[4:5], 0, v12
	s_nop 1
	v_cndmask_b32_e64 v3, v3, v9, s[4:5]
	v_mul_f32_e32 v7, 0x37800000, v3
	v_cndmask_b32_e32 v3, v3, v7, vcc
	v_cmp_class_f32_e32 vcc, v2, v205
	s_nop 1
	v_cndmask_b32_e32 v2, v3, v2, vcc
	v_div_scale_f32 v3, s[4:5], v2, v2, 1.0
	v_rcp_f32_e32 v7, v3
	v_div_scale_f32 v9, vcc, 1.0, v2, 1.0
	v_fma_f32 v11, -v3, v7, 1.0
	v_fmac_f32_e32 v7, v11, v7
	v_mul_f32_e32 v11, v9, v7
	v_fma_f32 v12, -v3, v11, v9
	v_fmac_f32_e32 v11, v12, v7
	v_fma_f32 v3, -v3, v11, v9
	v_div_fmas_f32 v3, v3, v7, v11
	v_div_fixup_f32 v3, v3, v2, 1.0
	v_mov_b32_e32 v30, v3
	s_branch .Lrstd_done_4

.Lrstd_done_4:
.LBB0_941:
	s_or_b64 exec, exec, s[6:7]
	v_add_u32_e32 v7, 0x400, v8
	v_mov_b32_e32 v2, s95
	v_cmp_gt_i32_e64 s[4:5], s10, v7
	s_and_saveexec_b64 s[8:9], s[4:5]
	s_cbranch_execz .LBB0_947
	v_ashrrev_i32_e32 v2, 8, v7
	v_mov_b64_e32 v[8:9], s[80:81]
	v_mad_i64_i32 v[8:9], s[6:7], v2, s63, v[8:9]
	s_mov_b64 s[6:7], 0xb00
	s_nop 0
	v_cmp_gt_i64_e32 vcc, s[6:7], v[8:9]
	s_and_saveexec_b64 s[6:7], vcc
	s_cbranch_execz .LBB0_944
	v_ashrrev_i32_e32 v2, 31, v8
	v_lshrrev_b32_e32 v2, 29, v2
	v_add_u32_e32 v2, v8, v2
	v_ashrrev_i32_e32 v6, 3, v2
	v_and_b32_e32 v2, -8, v2
	v_sub_u32_e32 v2, v8, v2
	v_cmp_gt_i32_e32 vcc, 0, v2
	s_mov_b32 s12, 0x2e8ba2e9
	s_nop 0
	v_cndmask_b32_e32 v7, v233, v234, vcc
	v_mul_lo_u32 v2, v2, v7
	v_add_u32_e32 v2, v2, v6
	v_mul_hi_i32 v6, v2, s12
	v_lshrrev_b32_e32 v7, 31, v6
	v_ashrrev_i32_e32 v6, 5, v6
	v_add_u32_e32 v6, v6, v7
	v_lshlrev_b32_e32 v7, 3, v6
	v_sub_u32_e32 v8, 0x80, v7
	v_min_i32_e32 v8, 8, v8
	v_sub_u32_e32 v9, 0, v8
	v_max_i32_e32 v8, v8, v9
	v_cvt_f32_u32_e32 v9, v8
	s_movk_i32 s12, 0xb0
	v_mul_lo_u32 v6, v6, s12
	v_sub_u32_e32 v2, v2, v6
	v_rcp_iflag_f32_e32 v9, v9
	v_sub_u32_e32 v11, 0, v2
	v_ashrrev_i32_e32 v6, 31, v2
	v_max_i32_e32 v2, v2, v11
	v_mul_f32_e32 v9, 0x4f7ffffe, v9
	v_cvt_u32_f32_e32 v9, v9
	v_sub_u32_e32 v11, 0, v8
	v_mul_lo_u32 v11, v11, v9
	v_mul_hi_u32 v11, v9, v11
	v_add_u32_e32 v9, v9, v11
	v_mul_hi_u32 v9, v2, v9
	v_mul_lo_u32 v9, v9, v8
	v_sub_u32_e32 v2, v2, v9
	v_sub_u32_e32 v9, v2, v8
	v_cmp_ge_u32_e32 vcc, v2, v8
	s_nop 1
	v_cndmask_b32_e32 v2, v2, v9, vcc
	v_sub_u32_e32 v9, v2, v8
	v_cmp_ge_u32_e32 vcc, v2, v8
	s_nop 1
	v_cndmask_b32_e32 v2, v2, v9, vcc
	v_xor_b32_e32 v2, v2, v6
	v_sub_u32_e32 v2, v2, v6
	v_add_u32_e32 v6, v7, v2
.LBB0_944:
	s_or_b64 exec, exec, s[6:7]
	v_ashrrev_i32_e32 v7, 31, v6
	v_lshlrev_b64 v[8:9], 14, v[6:7]
	v_lshl_add_u64 v[8:9], v[4:5], 0, v[8:9]
	v_cmp_ne_u64_e32 vcc, v[8:9], v[28:29]
	s_cbranch_vccz .Lrstd_same_5
	v_mov_b32_e32 v28, v8
	v_mov_b32_e32 v29, v9
	global_load_dwordx4 v[12:15], v[8:9], off
	global_load_dwordx4 v[16:19], v[8:9], off offset:16
	global_load_dwordx4 v[20:23], v[8:9], off offset:32
	global_load_dwordx4 v[24:27], v[8:9], off offset:48
	s_waitcnt vmcnt(0) lgkmcnt(0)
	v_mov_b32_e32 v8, v13
	v_mov_b32_e32 v9, v14
	v_mov_b32_e32 v13, v15
	v_mov_b32_e32 v14, v17
	v_mov_b32_e32 v15, v18
	v_mov_b32_e32 v17, v19
	v_pk_add_f32 v[8:9], v[8:9], v[12:13]
	v_pk_add_f32 v[12:13], v[14:15], v[16:17]
	v_pk_add_f32 v[8:9], v[8:9], v[8:9] op_sel:[0,1] op_sel_hi:[1,0]
	v_pk_add_f32 v[12:13], v[12:13], v[12:13] op_sel:[0,1] op_sel_hi:[1,0]
	v_add_f32_e32 v18, v20, v21
	v_add_f32_e32 v20, v22, v23
	v_mov_b32_e32 v19, v26
	v_mov_b32_e32 v21, v27
	v_mov_b32_e32 v9, v24
	v_mov_b32_e32 v13, v25
	v_pk_add_f32 v[14:15], v[18:19], v[20:21]
	v_pk_add_f32 v[8:9], v[8:9], v[12:13]
	s_nop 0
	v_pk_add_f32 v[8:9], v[8:9], v[14:15]
	s_nop 0
	v_add_f32_e32 v2, v8, v9
	v_fmamk_f32 v2, v2, 0x3a800000, v218
	v_mul_f32_e32 v7, 0x4f800000, v2
	v_cmp_gt_f32_e32 vcc, s79, v2
	s_nop 1
	v_cndmask_b32_e32 v2, v2, v7, vcc
	v_sqrt_f32_e32 v7, v2
	s_nop 0
	v_add_u32_e32 v8, -1, v7
	v_add_u32_e32 v9, 1, v7
	v_fma_f32 v11, -v8, v7, v2
	v_fma_f32 v12, -v9, v7, v2
	v_cmp_ge_f32_e64 s[6:7], 0, v11
	s_nop 1
	v_cndmask_b32_e64 v7, v7, v8, s[6:7]
	v_cmp_lt_f32_e64 s[6:7], 0, v12
	s_nop 1
	v_cndmask_b32_e64 v7, v7, v9, s[6:7]
	v_mul_f32_e32 v8, 0x37800000, v7
	v_cndmask_b32_e32 v7, v7, v8, vcc
	v_cmp_class_f32_e32 vcc, v2, v205
	s_nop 1
	v_cndmask_b32_e32 v2, v7, v2, vcc
	v_div_scale_f32 v7, s[6:7], v2, v2, 1.0
	v_rcp_f32_e32 v8, v7
	v_div_scale_f32 v9, vcc, 1.0, v2, 1.0
	v_fma_f32 v11, -v7, v8, 1.0
	v_fmac_f32_e32 v8, v11, v8
	v_mul_f32_e32 v11, v9, v8
	v_fma_f32 v12, -v7, v11, v9
	v_fmac_f32_e32 v11, v12, v8
	v_fma_f32 v7, -v7, v11, v9
	v_div_fmas_f32 v7, v7, v8, v11
	v_div_fixup_f32 v2, v7, v2, 1.0
	v_mov_b32_e32 v30, v2
	s_branch .Lrstd_done_5

.Lrstd_done_5:
	s_or_b64 exec, exec, s[8:9]
	s_and_saveexec_b64 s[6:7], s[2:3]
	s_cbranch_execnz .LBB0_948
